# speedup vs baseline: 1.0128x; 1.0036x over previous
;   __device__ __forceinline__ const float* in(int i) const { return reinterpret_cast<const float*>(ld64(i * 8)); }
;   __device__ __forceinline__ unsigned char* ws() const { return reinterpret_cast<unsigned char*>(ld64(27 * 8)); }
; __device__ __forceinline__ void phase_convert(const PRef& p) {
;   unsigned char* ws = p.ws();
;   constexpr int U0 = 704, U1 = U0 + 352, U2 = U1 + 704, U3 = U2 + 352, U4 = U3 + 384, U5 = U4 + 128;
;   for (int u = blockIdx.x; u < U5; u += gridDim.x) {
;     if (u < U0)      convert_weight(p.in(7), p.in(8), true, 1024, DFF, 5632, (bf16*)(ws + WS_W1A), u);
;     else if (u < U1) convert_weight(p.in(9), nullptr, false, DFF, 1024, 1024, (bf16*)(ws + WS_WD1), u - U0);
;     else if (u < U2) convert_weight(p.in(21), p.in(22), true, 1024, DFF, 5632, (bf16*)(ws + WS_W1B), u - U1);
;     else if (u < U3) convert_weight(p.in(23), nullptr, false, DFF, 1024, 1024, (bf16*)(ws + WS_WD2), u - U2);
;     else if (u < U4) convert_weight(p.in(12), nullptr, false, 1024, 3072, 3072, (bf16*)(ws + WS_WIN), u - U3);
;     else             convert_weight(p.in(18), nullptr, false, 1024, 1024, 1024, (bf16*)(ws + WS_WOUT), u - U4);
;   }
.LBB0_1138:
	v_readlane_b32 s0, v254, 10
	v_readlane_b32 s1, v254, 0
	s_mov_b32 s16, -1
	s_mov_b32 s17, 0
	s_mov_b32 s101, 0
	s_cmp_eq_u32 s0, 1
	s_cselect_b32 s16, 0x96, s16
	s_cselect_b32 s17, 0x420, s17
	s_cselect_b32 s101, 0x6e0, s101
	s_cmp_eq_u32 s0, 8
	s_cselect_b32 s16, 0x96, s16
	s_cselect_b32 s17, 0x6e0, s17
	s_cselect_b32 s101, 0x840, s101
	s_cmp_eq_u32 s0, 2
	s_cselect_b32 s16, 0x2c, s16
	s_cselect_b32 s17, 0x840, s17
	s_cselect_b32 s101, 0x9c0, s101
	s_cmp_eq_u32 s0, 4
	s_cselect_b32 s16, 0x30, s16
	s_cselect_b32 s17, 0x9c0, s17
	s_cselect_b32 s101, 0xa40, s101
	s_cmp_lt_u32 s1, s16
	s_cbranch_scc1 .Lmy_cv_return
	v_readlane_b32 s100, v254, 1
	s_sub_i32 s100, s100, s16
	s_sub_i32 s18, s1, s16
	s_add_i32 s18, s18, s17
	s_cmp_ge_i32 s18, s101
	s_cbranch_scc1 .Lmy_cv_return
	s_lshl_b32 s17, s18, 8
	s_or_b32 s17, s17, 15
	s_lshl_b32 s16, s18, 3
	s_add_i32 s16, s16, 0x7be00
	v_mov_b32_e32 v2, 0x23fd8
	ds_read_b64 v[2:3], v2
	s_waitcnt lgkmcnt(0)
	v_readfirstlane_b32 s4, v2
	v_readfirstlane_b32 s5, v3
	s_branch .Lmy_cv_entry

;   __device__ __forceinline__ const float* in(int i) const { return reinterpret_cast<const float*>(ld64(i * 8)); }
;   __device__ __forceinline__ unsigned char* ws() const { return reinterpret_cast<unsigned char*>(ld64(27 * 8)); }
; __device__ __forceinline__ void phase_convert(const PRef& p) {
;   unsigned char* ws = p.ws();
;   constexpr int U0 = 704, U1 = U0 + 352, U2 = U1 + 704, U3 = U2 + 352, U4 = U3 + 384, U5 = U4 + 128;
;   for (int u = blockIdx.x; u < U5; u += gridDim.x) {
;     if (u < U0)      convert_weight(p.in(7), p.in(8), true, 1024, DFF, 5632, (bf16*)(ws + WS_W1A), u);
;     else if (u < U1) convert_weight(p.in(9), nullptr, false, DFF, 1024, 1024, (bf16*)(ws + WS_WD1), u - U0);
;     else if (u < U2) convert_weight(p.in(21), p.in(22), true, 1024, DFF, 5632, (bf16*)(ws + WS_W1B), u - U1);
;     else if (u < U3) convert_weight(p.in(23), nullptr, false, DFF, 1024, 1024, (bf16*)(ws + WS_WD2), u - U2);
;     else if (u < U4) convert_weight(p.in(12), nullptr, false, 1024, 3072, 3072, (bf16*)(ws + WS_WIN), u - U3);
;     else             convert_weight(p.in(18), nullptr, false, 1024, 1024, 1024, (bf16*)(ws + WS_WOUT), u - U4);
;   }
.LBB0_1143:
	s_or_b64 exec, exec, s[0:1]
	s_movk_i32 s101, 0x420
	s_mov_b64 s[0:1], src_shared_base
	v_readlane_b32 s0, v254, 5
	s_cmp_lg_u32 s0, -1
	s_cselect_b32 s0, s0, 0
	v_mov_b32_e32 v2, s0
	v_readlane_b32 s0, v254, 6
	s_cselect_b32 s4, s1, 0
	s_cmp_lg_u32 s0, -1
	v_mov_b32_e32 v3, s4
	s_cselect_b32 s0, s0, 0
	s_cselect_b32 s1, s1, 0
	flat_load_dword v0, v[2:3] sc0 sc1
	s_waitcnt vmcnt(0)
	v_mov_b32_e32 v2, s0
	v_mov_b32_e32 v3, s1
	flat_load_dword v2, v[2:3] sc0 sc1
	s_waitcnt vmcnt(0)
	v_readlane_b32 s0, v254, 19
	v_readlane_b32 s1, v254, 20
	s_andn2_b64 vcc, exec, s[0:1]
	s_waitcnt lgkmcnt(0)
	v_readfirstlane_b32 s4, v0
	v_readfirstlane_b32 s5, v2
	s_cbranch_vccnz .LBB0_1166
	v_readlane_b32 s100, v254, 1
	v_readlane_b32 s16, v254, 43
	v_readlane_b32 s17, v254, 41
	v_readlane_b32 s18, v254, 0

;   __device__ __forceinline__ const float* in(int i) const { return reinterpret_cast<const float*>(ld64(i * 8)); }
;   __device__ __forceinline__ unsigned char* ws() const { return reinterpret_cast<unsigned char*>(ld64(27 * 8)); }
; __device__ __forceinline__ int opaque_tid() { int t = threadIdx.x; asm volatile("" : "+v"(t)); return t; }
; __device__ __forceinline__ void convert_weight(const float* __restrict__ srcA, const float* __restrict__ srcB, bool act, int K, int N, int P,
;                                bf16* __restrict__ dst, int unit) {
;   const int tidx = opaque_tid();
;   const int kblocks = K / 256;
;   const int pg = unit / kblocks, kb = unit % kblocks;
;   const int tid = tidx, pl = tid & 31, kg = tid >> 5;
;   const int p = pg * 32 + pl;
;   const float* src; int col;
;   if (act) {
;     int t = p >> 8, half = (p >> 7) & 1, c = p & 127;
;     col = t * 128 + (c & ~31) + lperm32(c & 31);
;     src = half ? srcB : srcA;
;   } else { col = (p & ~31) + lperm32(p & 31); src = srcA; }
;   const int k0 = kb * 256 + kg * 16;
;   float v[16];
; #pragma unroll
;   for (int i = 0; i < 16; ++i) v[i] = __builtin_nontemporal_load(src + (size_t)(k0 + i) * N + col);
;   u32x4 a = {cvtpk(v[0], v[1]), cvtpk(v[2], v[3]), cvtpk(v[4], v[5]), cvtpk(v[6], v[7])};
;   u32x4 b = {cvtpk(v[8], v[9]), cvtpk(v[10], v[11]), cvtpk(v[12], v[13]), cvtpk(v[14], v[15])};
;   u32x4* d = reinterpret_cast<u32x4*>(dst + (size_t)p * K + k0);
;   d[0] = a; d[1] = b;
;   (void)P;
; }
; __device__ __forceinline__ void phase_convert(const PRef& p) {
;     ...
;   for (int u = blockIdx.x; u < U5; u += gridDim.x) {
;     if (u < U0)      convert_weight(p.in(7), p.in(8), true, 1024, DFF, 5632, (bf16*)(ws + WS_W1A), u);
;     else if (u < U1) convert_weight(p.in(9), nullptr, false, DFF, 1024, 1024, (bf16*)(ws + WS_WD1), u - U0);
;     else if (u < U2) convert_weight(p.in(21), p.in(22), true, 1024, DFF, 5632, (bf16*)(ws + WS_W1B), u - U1);
;     else if (u < U3) convert_weight(p.in(23), nullptr, false, DFF, 1024, 1024, (bf16*)(ws + WS_WD2), u - U2);
;     else if (u < U4) convert_weight(p.in(12), nullptr, false, 1024, 3072, 3072, (bf16*)(ws + WS_WIN), u - U3);
;     else             convert_weight(p.in(18), nullptr, false, 1024, 1024, 1024, (bf16*)(ws + WS_WOUT), u - U4);
.LBB0_1145:
	s_add_i32 s18, s18, s100
	s_lshl_b32 s0, s100, 8
	s_add_i32 s17, s17, s0
	s_lshl_b32 s0, s100, 3
	s_add_i32 s16, s16, s0
	s_cmp_lt_i32 s18, s101
	v_readlane_b32 s1, v254, 2
	flat_store_dwordx4 v[6:7], v[2:5] offset:16
	s_cbranch_scc0 .LBB0_1166
.LBB0_1146:
	s_cmpk_gt_i32 s18, 0x2bf
	s_mov_b64 s[0:1], -1
	s_cbranch_scc0 .LBB0_1164
	s_cmpk_gt_u32 s18, 0x41f
	s_cbranch_scc0 .LBB0_1161
	s_cmpk_gt_u32 s18, 0x6df
	s_cbranch_scc0 .LBB0_1158
	s_cmpk_gt_u32 s18, 0x83f
	s_cbranch_scc0 .LBB0_1155
	s_cmpk_gt_u32 s18, 0x9bf
	s_cbranch_scc0 .LBB0_1152
	s_mov_b64 s[0:1], src_shared_base
	s_add_i32 s0, 0, 0x23f90
	s_cmp_lg_u32 s0, -1
	s_cselect_b32 s0, s0, 0
	s_cselect_b32 s19, s1, 0
	v_mov_b32_e32 v2, s0
	s_add_i32 s0, 0, 0x23f94
	s_cmp_lg_u32 s0, -1
	v_mov_b32_e32 v3, s19
	s_cselect_b32 s0, s0, 0
	s_cselect_b32 s1, s1, 0
	flat_load_dword v34, v[2:3] sc0 sc1
	s_waitcnt vmcnt(0)
	v_mov_b32_e32 v2, s0
	v_mov_b32_e32 v3, s1
	flat_load_dword v35, v[2:3] sc0 sc1
	s_waitcnt vmcnt(0)
	v_mov_b32_e32 v38, v171
	s_add_i32 s0, s16, 0xfff84400
	s_add_i32 s1, s17, -15
	s_and_b32 s19, s0, 0x7e0
	v_lshlrev_b32_e32 v0, 1, v38
	v_ashrrev_i32_e32 v3, 1, v38
	s_and_b32 s0, s1, 0x300
	v_bfe_u32 v2, v38, 4, 1
	v_and_b32_e32 v0, 30, v0
	v_and_b32_e32 v3, -16, v3
	v_or3_b32 v0, v2, v0, s19
	v_add_u32_e32 v2, s0, v3
	v_or_b32_e32 v4, 1, v2
	v_or_b32_e32 v8, 3, v2
	v_or_b32_e32 v10, 4, v2
	v_or_b32_e32 v12, 5, v2
	v_or_b32_e32 v14, 6, v2
	v_or_b32_e32 v16, 7, v2
	v_or_b32_e32 v18, 8, v2
	v_or_b32_e32 v20, 9, v2
	v_or_b32_e32 v22, 10, v2
	v_or_b32_e32 v26, 12, v2
	v_lshlrev_b32_e32 v0, 2, v0
	v_ashrrev_i32_e32 v3, 31, v2
	v_or_b32_e32 v6, 2, v2
	v_or_b32_e32 v24, 11, v2
	v_or_b32_e32 v28, 13, v2
	v_or_b32_e32 v30, 14, v2
	v_ashrrev_i32_e32 v5, 31, v4
	v_ashrrev_i32_e32 v9, 31, v8
	v_ashrrev_i32_e32 v11, 31, v10
	v_ashrrev_i32_e32 v13, 31, v12
	v_ashrrev_i32_e32 v15, 31, v14
	v_ashrrev_i32_e32 v17, 31, v16
	v_ashrrev_i32_e32 v19, 31, v18
	v_ashrrev_i32_e32 v21, 31, v20
	v_ashrrev_i32_e32 v23, 31, v22
	v_ashrrev_i32_e32 v27, 31, v26
	v_or_b32_e32 v36, 15, v2
	v_lshlrev_b64 v[32:33], 12, v[2:3]
	v_ashrrev_i32_e32 v7, 31, v6
	v_ashrrev_i32_e32 v25, 31, v24
	v_ashrrev_i32_e32 v29, 31, v28
	v_ashrrev_i32_e32 v31, 31, v30
	v_lshlrev_b64 v[4:5], 12, v[4:5]
	v_lshlrev_b64 v[8:9], 12, v[8:9]
	v_lshlrev_b64 v[10:11], 12, v[10:11]
	v_lshlrev_b64 v[12:13], 12, v[12:13]
	v_lshlrev_b64 v[14:15], 12, v[14:15]
	v_lshlrev_b64 v[16:17], 12, v[16:17]
	v_lshlrev_b64 v[18:19], 12, v[18:19]
	v_lshlrev_b64 v[20:21], 12, v[20:21]
	v_lshlrev_b64 v[22:23], 12, v[22:23]
	v_lshlrev_b64 v[26:27], 12, v[26:27]
	v_ashrrev_i32_e32 v37, 31, v36
	v_lshlrev_b64 v[6:7], 12, v[6:7]
	v_lshlrev_b64 v[24:25], 12, v[24:25]
	v_lshlrev_b64 v[28:29], 12, v[28:29]
	v_lshlrev_b64 v[30:31], 12, v[30:31]
	v_lshlrev_b64 v[36:37], 12, v[36:37]
	s_waitcnt lgkmcnt(0)
	v_readfirstlane_b32 s0, v34
	v_readfirstlane_b32 s1, v35
	s_nop 1
	v_lshl_add_u64 v[34:35], s[0:1], 0, v[0:1]
	v_lshl_add_u64 v[32:33], v[34:35], 0, v[32:33]
	v_lshl_add_u64 v[4:5], v[34:35], 0, v[4:5]
	v_lshl_add_u64 v[8:9], v[34:35], 0, v[8:9]
	v_lshl_add_u64 v[10:11], v[34:35], 0, v[10:11]
	v_lshl_add_u64 v[12:13], v[34:35], 0, v[12:13]
	v_lshl_add_u64 v[14:15], v[34:35], 0, v[14:15]
	v_lshl_add_u64 v[16:17], v[34:35], 0, v[16:17]
	v_lshl_add_u64 v[18:19], v[34:35], 0, v[18:19]
	v_lshl_add_u64 v[20:21], v[34:35], 0, v[20:21]
	v_lshl_add_u64 v[22:23], v[34:35], 0, v[22:23]
	v_lshl_add_u64 v[26:27], v[34:35], 0, v[26:27]
	v_lshl_add_u64 v[6:7], v[34:35], 0, v[6:7]
	v_lshl_add_u64 v[24:25], v[34:35], 0, v[24:25]
	v_lshl_add_u64 v[28:29], v[34:35], 0, v[28:29]
	v_lshl_add_u64 v[36:37], v[34:35], 0, v[36:37]
	flat_load_dword v32, v[32:33] nt
	s_nop 0
	flat_load_dword v33, v[4:5] nt
	s_nop 0
	flat_load_dword v9, v[8:9] nt
	s_nop 0
	flat_load_dword v12, v[12:13] nt
	s_nop 0
	flat_load_dword v13, v[16:17] nt
	s_nop 0
	flat_load_dword v14, v[14:15] nt
	s_nop 0
	flat_load_dword v10, v[10:11] nt
	s_nop 0
	flat_load_dword v11, v[6:7] nt
	flat_load_dword v15, v[20:21] nt
	flat_load_dword v16, v[22:23] nt
	flat_load_dword v17, v[36:37] nt
	s_nop 0
	flat_load_dword v20, v[28:29] nt
	flat_load_dword v21, v[24:25] nt
	s_nop 0
	flat_load_dword v18, v[18:19] nt
	v_lshl_add_u64 v[4:5], v[34:35], 0, v[30:31]
	flat_load_dword v19, v[26:27] nt
	flat_load_dword v22, v[4:5] nt
	v_and_or_b32 v0, v38, 31, s19
	v_lshlrev_b32_e32 v0, 11, v0
	v_lshl_add_u64 v[4:5], s[6:7], 0, v[0:1]
	v_lshl_add_u64 v[6:7], v[2:3], 1, v[4:5]
	s_mov_b64 s[0:1], 0
	s_waitcnt vmcnt(0) lgkmcnt(0)
	v_cvt_pk_bf16_f32 v8, v32, v33
	v_cvt_pk_bf16_f32 v9, v11, v9
	v_cvt_pk_bf16_f32 v10, v10, v12
	v_cvt_pk_bf16_f32 v11, v14, v13
	v_cvt_pk_bf16_f32 v2, v18, v15
	v_cvt_pk_bf16_f32 v3, v16, v21
	v_cvt_pk_bf16_f32 v4, v19, v20
	v_cvt_pk_bf16_f32 v5, v22, v17
	flat_store_dwordx4 v[6:7], v[8:11]

;   __device__ __forceinline__ const float* in(int i) const { return reinterpret_cast<const float*>(ld64(i * 8)); }
;   __device__ __forceinline__ float* out() const { return reinterpret_cast<float*>(ld64(26 * 8)); }
;   __device__ __forceinline__ unsigned char* ws() const { return reinterpret_cast<unsigned char*>(ld64(27 * 8)); }
; __device__ __forceinline__ int opaque_tid() { int t = threadIdx.x; asm volatile("" : "+v"(t)); return t; }
; template <int MODE>
; __device__ __forceinline__ void phase_rows(const PRef& p, const float* __restrict__ vsrc, const float* __restrict__ g1, const float* __restrict__ g2, float coef, int nsplit) {
;   const int tidx = opaque_tid();
;   const int lane = tidx & 63, wave = tidx >> 6;
;   bf16* xn = (bf16*)(p.ws() + WS_XN);
;   float* hbuf = p.out() + O_Y;
;   const float* xp = p.in(0); const float* xs_ = p.in(1);
;   for (int row = blockIdx.x * 8 + wave; row < MT; row += gridDim.x * 8) {
;     float4 h[4];
;     if (MODE == 0) {
;       const float4* xs = reinterpret_cast<const float4*>(row < MP ? xp + (size_t)row * DM : xs_ + (size_t)(row - MP) * DM);
; #pragma unroll
;       for (int i = 0; i < 4; ++i) { const f32x4v t = __builtin_nontemporal_load(reinterpret_cast<const f32x4v*>(xs) + lane + 64 * i); h[i] = make_float4(t[0], t[1], t[2], t[3]); }
.LBB0_1166:
	v_readlane_b32 s0, v254, 10
	s_cmp_lg_u32 s0, 0
	s_cbranch_scc1 .Lmy_cv_return
	s_add_i32 s0, 0, 0x23f30
	s_cmp_lg_u32 s0, -1
	s_cselect_b32 s0, s0, 0
	s_mov_b64 s[4:5], src_shared_base
	s_cselect_b32 s1, s5, 0
	v_mov_b32_e32 v2, s0
	s_add_i32 s0, 0, 0x23f34
	s_cmp_lg_u32 s0, -1
	v_mov_b32_e32 v3, s1
	s_cselect_b32 s0, s0, 0
	s_cselect_b32 s1, s5, 0
	flat_load_dword v0, v[2:3] sc0 sc1
	s_waitcnt vmcnt(0)
	v_mov_b32_e32 v2, s0
	v_mov_b32_e32 v3, s1
	flat_load_dword v2, v[2:3] sc0 sc1
	s_waitcnt vmcnt(0)
	v_readlane_b32 s0, v254, 5
	s_cmp_lg_u32 s0, -1
	s_cselect_b32 s0, s0, 0
	s_cselect_b32 s1, s5, 0
	v_mov_b32_e32 v3, s1
	s_waitcnt lgkmcnt(0)
	v_readfirstlane_b32 s8, v0
	v_mov_b32_e32 v0, v171
	v_readfirstlane_b32 s9, v2
	v_mov_b32_e32 v2, s0
	v_readlane_b32 s0, v254, 6
	s_cmp_lg_u32 s0, -1
	s_cselect_b32 s0, s0, 0
	s_cselect_b32 s1, s5, 0
	flat_load_dword v5, v[2:3] sc0 sc1
	s_waitcnt vmcnt(0)
	v_mov_b32_e32 v2, s0
	v_mov_b32_e32 v3, s1
	flat_load_dword v2, v[2:3] sc0 sc1
	s_waitcnt vmcnt(0)
	s_add_i32 s0, 0, 0x23fd0
	s_cmp_lg_u32 s0, -1
	s_cselect_b32 s0, s0, 0
	s_cselect_b32 s1, s5, 0
	v_mov_b32_e32 v3, s1
	v_ashrrev_i32_e32 v4, 6, v0
	s_waitcnt lgkmcnt(0)
	v_readfirstlane_b32 s10, v5
	v_readfirstlane_b32 s11, v2
	v_mov_b32_e32 v2, s0
	s_add_i32 s0, 0, 0x23fd4
	s_cmp_lg_u32 s0, -1
	flat_load_dword v2, v[2:3] sc0 sc1
	s_waitcnt vmcnt(0)
	s_cselect_b32 s0, s0, 0
	s_cselect_b32 s1, s5, 0
	s_waitcnt lgkmcnt(0)
	v_mov_b32_e32 v2, s0
	s_add_i32 s0, 0, 0x23f00
	v_mov_b32_e32 v3, s1
	s_cmp_lg_u32 s0, -1
	flat_load_dword v2, v[2:3] sc0 sc1
	s_waitcnt vmcnt(0)
	s_cselect_b32 s0, s0, 0
	s_cselect_b32 s1, s5, 0
	s_waitcnt lgkmcnt(0)
	v_mov_b32_e32 v2, s0
	s_add_i32 s0, 0, 0x23f04
	s_cmp_lg_u32 s0, -1
	v_mov_b32_e32 v3, s1
	s_cselect_b32 s0, s0, 0
	s_cselect_b32 s1, s5, 0
	flat_load_dword v5, v[2:3] sc0 sc1
	s_waitcnt vmcnt(0)
	v_mov_b32_e32 v2, s0
	v_mov_b32_e32 v3, s1
	flat_load_dword v2, v[2:3] sc0 sc1
	s_waitcnt vmcnt(0)
	s_add_i32 s4, 0, 0x23f08
	s_cmp_lg_u32 s4, -1
	s_cselect_b32 s4, s4, 0
	s_cselect_b32 s6, s5, 0
	v_mov_b32_e32 v3, s6
	v_readlane_b32 s6, v254, 42
	s_waitcnt lgkmcnt(0)
	v_readfirstlane_b32 s0, v5
	v_add_u32_e32 v10, s6, v4
	s_movk_i32 s6, 0x4100
	v_readfirstlane_b32 s1, v2
	v_mov_b32_e32 v2, s4
	s_add_i32 s4, 0, 0x23f0c
	s_cmp_lg_u32 s4, -1
	s_cselect_b32 s4, s4, 0
	s_cselect_b32 s5, s5, 0
	flat_load_dword v5, v[2:3] sc0 sc1
	s_waitcnt vmcnt(0)
	v_mov_b32_e32 v2, s4
	v_mov_b32_e32 v3, s5
	flat_load_dword v2, v[2:3] sc0 sc1
	s_waitcnt vmcnt(0)
	v_cmp_gt_i32_e32 vcc, s6, v10
	s_waitcnt lgkmcnt(0)
	v_readfirstlane_b32 s4, v5
	v_readfirstlane_b32 s5, v2
	s_and_saveexec_b64 s[6:7], vcc
	s_cbranch_execz .LBB0_1173
	v_and_b32_e32 v6, 63, v0
	v_lshlrev_b32_e32 v0, 4, v6
	v_lshl_add_u64 v[12:13], s[8:9], 0, v[0:1]
	flat_load_dwordx4 v[2:5], v[12:13]
	flat_load_dwordx4 v[228:231], v[12:13] offset:1024
	flat_load_dwordx4 v[232:235], v[12:13] offset:2048
	flat_load_dwordx4 v[236:239], v[12:13] offset:3072
	v_xor_b32_e32 v0, 32, v193
	v_cmp_lt_i32_e32 vcc, v0, v195
	s_mov_b64 s[8:9], 0x2a00000
	s_nop 0
	v_cndmask_b32_e32 v0, v193, v0, vcc
	v_cmp_lt_i32_e32 vcc, v253, v195
	v_lshlrev_b32_e32 v16, 2, v0
	s_nop 0
	v_cndmask_b32_e32 v0, v193, v253, vcc
	v_cmp_lt_i32_e32 vcc, v210, v195
	v_lshlrev_b32_e32 v17, 2, v0
	s_nop 0
	v_cndmask_b32_e32 v0, v193, v210, vcc
	v_lshlrev_b32_e32 v18, 2, v0
	v_xor_b32_e32 v0, 4, v193
	v_cmp_lt_i32_e32 vcc, v0, v195
	s_nop 1
	v_cndmask_b32_e32 v0, v193, v0, vcc
	v_lshlrev_b32_e32 v19, 2, v0
	v_xor_b32_e32 v0, 2, v193
	v_cmp_lt_i32_e32 vcc, v0, v195
	s_nop 1
	v_cndmask_b32_e32 v0, v193, v0, vcc
	v_lshlrev_b32_e32 v20, 2, v0
	v_xor_b32_e32 v0, 1, v193
	v_cmp_lt_i32_e32 vcc, v0, v195
	s_nop 1
	v_cndmask_b32_e32 v0, v193, v0, vcc
	v_lshlrev_b32_e32 v21, 2, v0
	v_lshlrev_b32_e32 v0, 3, v6
	v_lshl_add_u64 v[8:9], s[10:11], 0, v[0:1]
	v_lshl_add_u64 v[14:15], v[8:9], 0, s[8:9]
	s_mov_b64 s[8:9], 0
	v_lshlrev_b32_e32 v0, 4, v6
	s_branch .LBB0_1169
